# SB loop: 64 canonicalizing v_max (x,x) before fminf(z,100) replaced by s_nop 0; v_min reads the MFMA result directly
# speedup vs baseline: 1.0258x; 1.0018x over previous
; DI unsigned pk_bf16(float lo, float hi) { f32x2 v = {lo, hi}; bf2_t b = __builtin_convertvector(v, bf2_t); return __builtin_bit_cast(unsigned, b); }
; DI float bf_lo(unsigned u) { return __uint_as_float(u << 16); }
; DI float bf_hi(unsigned u) { return __uint_as_float(u & 0xffff0000u); }
; DI int crow(int i, int h) { return (i & 3) + 8 * (i >> 2) + 4 * h; }
; DI float fast_exp2(float x) { return __builtin_amdgcn_exp2f(x); }
; DI float fast_log2(float x) { return __builtin_amdgcn_logf(x); }
; #define AT_LOAD(SET, IT) { const int kl_ = AT_KB(IT); \
;     _Pragma("unroll") for (int i = 0; i < KPT; ++i) kreg[SET][i] = *(const u32x4*)(Kg + (size_t)kl_ * DQK + (tid + 256 * i) * 8); \
;     _Pragma("unroll") for (int i = 0; i < 2; ++i) vreg[SET][i] = *(const u32x4*)(Vg + (size_t)kl_ * 64 + (tid + 256 * i) * 8); \
;     __builtin_amdgcn_sched_barrier(0); }
; template <int DQK, bool SB, bool SMAX>
; DI void attn_item(const Params& p, char* smem, int bh, int qb, float Mb) {
;     ...
;     AT_WRITE(0, st2 ^ 1)
;     AT_LOAD(0, (it + 2 < nt) ? it + 2 : nt - 1)
;     if (active) {
;       const bool diag = (kb0 + 64 > qw0);
;       bf16x8 pk[4];
;     ...
;           for (int i2 = 0; i2 < 8; ++i2) {
;             float lk[2];
; #pragma unroll
;             for (int e = 0; e < 2; ++e) {
;               const int i = 2 * i2 + e;
;               const float z = fminf(st[kb][i], 100.f);
;               const int key = kb0 + kb * 32 + crow(i, h);
;               const bool valid = !diag || (key < query);
;               float l = -fast_log2(1.f + fast_exp2(z));
;               l = valid ? l : 0.f;
;               lk[e] = l;
;               tsum += l;
;               ca[kb][i] = z + carry;
;             }
;             const unsigned hp = pk_bf16(lk[0], lk[1]);
;             const unsigned lp = pk_bf16(lk[0] - bf_lo(hp), lk[1] - bf_hi(hp));
;             const int kk = kb * 2 + (i2 >> 2), w = i2 & 3;
;             hi[kk][2 * w] = (short)(hp & 0xffffu); hi[kk][2 * w + 1] = (short)(hp >> 16);
;             lo[kk][2 * w] = (short)(lp & 0xffffu); lo[kk][2 * w + 1] = (short)(lp >> 16);
;           }
.LBB0_435:
	s_or_b64 exec, exec, s[2:3]
	s_cmp_lt_u32 s4, s1
	s_cselect_b32 s2, s78, 0
	s_ashr_i32 s3, s2, 31
	s_lshl_b64 s[2:3], s[2:3], 7
	v_lshl_add_u64 v[80:81], v[148:149], 0, s[2:3]
	s_waitcnt vmcnt(3)
	ds_write_b128 v203, v[120:123] offset:9216
	s_waitcnt vmcnt(2)
	ds_write_b128 v204, v[124:127] offset:9216
	s_waitcnt vmcnt(1)
	ds_write_b128 v203, v[128:131] offset:27648
	s_waitcnt vmcnt(0)
	ds_write_b128 v204, v[132:135] offset:27648
	v_add_co_u32_e32 v82, vcc, 0x1000, v80
	s_nop 1
	v_addc_co_u32_e32 v83, vcc, 0, v81, vcc
	global_load_dwordx4 v[120:123], v[80:81], off
	global_load_dwordx4 v[124:127], v[82:83], off
	v_lshl_add_u64 v[80:81], v[150:151], 0, s[2:3]
	v_add_co_u32_e32 v82, vcc, 0x1000, v80
	s_nop 1
	v_addc_co_u32_e32 v83, vcc, 0, v81, vcc
	global_load_dwordx4 v[128:131], v[80:81], off
	global_load_dwordx4 v[132:135], v[82:83], off
	s_and_saveexec_b64 s[80:81], s[12:13]
	s_cbranch_execz .LBB0_437
	s_nop 0
	v_add_u32_e32 v143, s78, v197
	v_min_f32_e32 v84, 0x42c80000, v64
	s_nop 0
	v_exp_f32_e32 v64, v84
	v_min_f32_e32 v85, 0x42c80000, v65
	v_add_u32_e32 v65, 0x81, v143
	v_cmp_lt_i32_e64 s[2:3], v65, v176
	v_exp_f32_e32 v65, v85
	v_add_f32_e32 v64, 1.0, v64
	v_log_f32_e32 v64, v64
	v_add_u32_e32 v80, 0x80, v143
	v_add_f32_e32 v65, 1.0, v65
	v_log_f32_e32 v65, v65
	v_cmp_le_i32_e64 s[44:45], s14, v181
	v_cmp_lt_i32_e32 vcc, v80, v176
	s_or_b64 vcc, s[44:45], vcc
	s_or_b64 s[12:13], s[44:45], s[2:3]
	v_cndmask_b32_e64 v64, 0, -v64, vcc
	v_add_f32_e32 v80, 0, v64
	v_cndmask_b32_e64 v65, 0, -v65, s[12:13]
	v_add_f32_e32 v81, v65, v80
	v_cvt_pk_bf16_f32 v80, v64, v65
	v_lshlrev_b32_e32 v82, 16, v80
	v_sub_f32_e32 v64, v64, v82
	v_and_b32_e32 v82, 0xffff0000, v80
	v_sub_f32_e32 v65, v65, v82
	v_cvt_pk_bf16_f32 v64, v64, v65
	s_nop 0
	v_min_f32_e32 v86, 0x42c80000, v66
	v_add_u32_e32 v65, 0x82, v143
	s_nop 0
	v_cmp_lt_i32_e64 s[2:3], v65, v176
	v_min_f32_e32 v87, 0x42c80000, v67
	v_add_u32_e32 v67, 0x83, v143
	s_or_b64 s[14:15], s[44:45], s[2:3]
	v_exp_f32_e32 v65, v86
	v_cmp_lt_i32_e64 s[2:3], v67, v176
	v_exp_f32_e32 v67, v87
	s_or_b64 s[16:17], s[44:45], s[2:3]
	v_add_f32_e32 v65, 1.0, v65
	v_log_f32_e32 v65, v65
	v_add_f32_e32 v67, 1.0, v67
	v_log_f32_e32 v67, v67
	s_nop 0
	v_cndmask_b32_e64 v65, 0, -v65, s[14:15]
	v_add_f32_e32 v66, v65, v81
	v_cndmask_b32_e64 v67, 0, -v67, s[16:17]
	v_cvt_pk_bf16_f32 v81, v65, v67
	v_lshlrev_b32_e32 v82, 16, v81
	v_sub_f32_e32 v65, v65, v82
	v_and_b32_e32 v82, 0xffff0000, v81
	v_add_f32_e32 v66, v67, v66
	v_sub_f32_e32 v67, v67, v82
	v_cvt_pk_bf16_f32 v65, v65, v67
	s_nop 0
	v_min_f32_e32 v88, 0x42c80000, v68
	v_add_u32_e32 v67, 0x88, v143
	s_nop 0
	v_cmp_lt_i32_e64 s[2:3], v67, v176
	v_min_f32_e32 v89, 0x42c80000, v69
	v_add_u32_e32 v68, 0x89, v143
	s_or_b64 s[18:19], s[44:45], s[2:3]
	v_exp_f32_e32 v67, v88
	v_cmp_lt_i32_e64 s[2:3], v68, v176
	v_exp_f32_e32 v68, v89
	s_or_b64 s[20:21], s[44:45], s[2:3]
	v_add_f32_e32 v67, 1.0, v67
	v_log_f32_e32 v67, v67
	v_add_f32_e32 v68, 1.0, v68
	v_log_f32_e32 v68, v68
	s_nop 0
	v_cndmask_b32_e64 v67, 0, -v67, s[18:19]
	v_add_f32_e32 v66, v67, v66
	v_cndmask_b32_e64 v68, 0, -v68, s[20:21]
	v_cvt_pk_bf16_f32 v82, v67, v68
	v_add_f32_e32 v69, v68, v66
	v_lshlrev_b32_e32 v66, 16, v82
	v_sub_f32_e32 v66, v67, v66
	v_and_b32_e32 v67, 0xffff0000, v82
	v_sub_f32_e32 v67, v68, v67
	v_cvt_pk_bf16_f32 v66, v66, v67
	s_nop 0
	v_min_f32_e32 v90, 0x42c80000, v70
	v_add_u32_e32 v67, 0x8a, v143
	v_cmp_lt_i32_e64 s[2:3], v67, v176
	v_exp_f32_e32 v67, v90
	s_or_b64 s[22:23], s[44:45], s[2:3]
	v_min_f32_e32 v156, 0x42c80000, v48
	v_min_f32_e32 v157, 0x42c80000, v49
	v_add_f32_e32 v67, 1.0, v67
	v_log_f32_e32 v67, v67
	v_add_u32_e32 v49, 0xa1, v143
	v_exp_f32_e32 v48, v156
	s_mov_b32 s97, s96
	v_cndmask_b32_e64 v67, 0, -v67, s[22:23]
	v_add_f32_e32 v68, v67, v69
	s_nop 0
	v_min_f32_e32 v91, 0x42c80000, v71
	v_add_u32_e32 v69, 0x8b, v143
	v_cmp_lt_i32_e64 s[2:3], v69, v176
	v_exp_f32_e32 v69, v91
	s_or_b64 s[24:25], s[44:45], s[2:3]
	v_add_f32_e32 v48, 1.0, v48
	v_log_f32_e32 v48, v48
	v_add_f32_e32 v69, 1.0, v69
	v_log_f32_e32 v69, v69
	s_mov_b32 s98, s96
	s_mov_b32 s99, s96
	v_cndmask_b32_e64 v69, 0, -v69, s[24:25]
	v_cvt_pk_bf16_f32 v83, v67, v69
	v_lshlrev_b32_e32 v70, 16, v83
	v_sub_f32_e32 v67, v67, v70
	v_and_b32_e32 v70, 0xffff0000, v83
	v_add_f32_e32 v68, v69, v68
	v_sub_f32_e32 v69, v69, v70
	v_cvt_pk_bf16_f32 v67, v67, v69
	s_nop 0
	v_min_f32_e32 v92, 0x42c80000, v72
	v_add_u32_e32 v69, 0x90, v143
	s_nop 0
	v_cmp_lt_i32_e64 s[2:3], v69, v176
	v_min_f32_e32 v93, 0x42c80000, v73
	v_add_u32_e32 v70, 0x91, v143
	s_or_b64 s[26:27], s[44:45], s[2:3]
	v_exp_f32_e32 v69, v92
	v_cmp_lt_i32_e64 s[2:3], v70, v176
	v_exp_f32_e32 v70, v93
	s_or_b64 s[28:29], s[44:45], s[2:3]
	v_add_f32_e32 v69, 1.0, v69
	v_log_f32_e32 v69, v69
	v_add_f32_e32 v70, 1.0, v70
	v_log_f32_e32 v70, v70
	v_cndmask_b32_e64 v69, 0, -v69, s[26:27]
	v_add_f32_e32 v68, v69, v68
	v_cndmask_b32_e64 v70, 0, -v70, s[28:29]
	v_cvt_pk_bf16_f32 v72, v69, v70
	v_add_f32_e32 v71, v70, v68
	v_lshlrev_b32_e32 v68, 16, v72
	v_sub_f32_e32 v68, v69, v68
	v_and_b32_e32 v69, 0xffff0000, v72
	v_sub_f32_e32 v69, v70, v69
	v_cvt_pk_bf16_f32 v68, v68, v69
	s_nop 0
	v_min_f32_e32 v94, 0x42c80000, v74
	v_add_u32_e32 v69, 0x92, v143
	v_cmp_lt_i32_e64 s[2:3], v69, v176
	v_exp_f32_e32 v69, v94
	s_or_b64 s[30:31], s[44:45], s[2:3]
	v_add_f32_e32 v69, 1.0, v69
	v_log_f32_e32 v69, v69
	s_nop 0
	v_cndmask_b32_e64 v69, 0, -v69, s[30:31]
	v_add_f32_e32 v70, v69, v71
	s_nop 0
	v_min_f32_e32 v95, 0x42c80000, v75
	v_add_u32_e32 v71, 0x93, v143
	v_cmp_lt_i32_e64 s[2:3], v71, v176
	v_exp_f32_e32 v71, v95
	s_or_b64 s[34:35], s[44:45], s[2:3]
; DI unsigned pk_bf16(float lo, float hi) { f32x2 v = {lo, hi}; bf2_t b = __builtin_convertvector(v, bf2_t); return __builtin_bit_cast(unsigned, b); }
; DI float bf_lo(unsigned u) { return __uint_as_float(u << 16); }
; DI float bf_hi(unsigned u) { return __uint_as_float(u & 0xffff0000u); }
; DI int crow(int i, int h) { return (i & 3) + 8 * (i >> 2) + 4 * h; }
; DI float fast_exp2(float x) { return __builtin_amdgcn_exp2f(x); }
; DI float fast_log2(float x) { return __builtin_amdgcn_logf(x); }
; template <int DQK, bool SB, bool SMAX>
; DI void attn_item(const Params& p, char* smem, int bh, int qb, float Mb) {
;     ...
;           for (int i2 = 0; i2 < 8; ++i2) {
;             float lk[2];
; #pragma unroll
;             for (int e = 0; e < 2; ++e) {
;               const int i = 2 * i2 + e;
;               const float z = fminf(st[kb][i], 100.f);
;               const int key = kb0 + kb * 32 + crow(i, h);
;               const bool valid = !diag || (key < query);
;               float l = -fast_log2(1.f + fast_exp2(z));
;               l = valid ? l : 0.f;
;               lk[e] = l;
;               tsum += l;
;               ca[kb][i] = z + carry;
;             }
;             const unsigned hp = pk_bf16(lk[0], lk[1]);
;             const unsigned lp = pk_bf16(lk[0] - bf_lo(hp), lk[1] - bf_hi(hp));
;             const int kk = kb * 2 + (i2 >> 2), w = i2 & 3;
;             hi[kk][2 * w] = (short)(hp & 0xffffu); hi[kk][2 * w + 1] = (short)(hp >> 16);
;             lo[kk][2 * w] = (short)(lp & 0xffffu); lo[kk][2 * w + 1] = (short)(lp >> 16);
;           }
	v_add_f32_e32 v71, 1.0, v71
	v_log_f32_e32 v71, v71
	s_nop 0
	v_cndmask_b32_e64 v71, 0, -v71, s[34:35]
	v_cvt_pk_bf16_f32 v73, v69, v71
	v_lshlrev_b32_e32 v74, 16, v73
	v_sub_f32_e32 v69, v69, v74
	v_and_b32_e32 v74, 0xffff0000, v73
	v_add_f32_e32 v70, v71, v70
	v_sub_f32_e32 v71, v71, v74
	v_cvt_pk_bf16_f32 v69, v69, v71
	s_nop 0
	v_min_f32_e32 v154, 0x42c80000, v76
	v_add_u32_e32 v71, 0x98, v143
	s_nop 0
	v_cmp_lt_i32_e64 s[2:3], v71, v176
	v_min_f32_e32 v155, 0x42c80000, v77
	v_add_u32_e32 v74, 0x99, v143
	s_or_b64 s[36:37], s[44:45], s[2:3]
	v_exp_f32_e32 v71, v154
	v_cmp_lt_i32_e64 s[2:3], v74, v176
	v_exp_f32_e32 v74, v155
	s_or_b64 s[38:39], s[44:45], s[2:3]
	v_add_f32_e32 v71, 1.0, v71
	v_log_f32_e32 v71, v71
	v_add_f32_e32 v74, 1.0, v74
	v_log_f32_e32 v74, v74
	v_cndmask_b32_e64 v71, 0, -v71, s[36:37]
	v_add_f32_e32 v70, v71, v70
	v_cndmask_b32_e64 v75, 0, -v74, s[38:39]
	v_cvt_pk_bf16_f32 v74, v71, v75
	v_add_f32_e32 v76, v75, v70
	v_lshlrev_b32_e32 v70, 16, v74
	v_sub_f32_e32 v70, v71, v70
	v_and_b32_e32 v71, 0xffff0000, v74
	v_sub_f32_e32 v71, v75, v71
	v_cvt_pk_bf16_f32 v70, v70, v71
	s_nop 0
	v_min_f32_e32 v158, 0x42c80000, v78
	v_add_u32_e32 v71, 0x9a, v143
	v_cmp_lt_i32_e64 s[2:3], v71, v176
	v_exp_f32_e32 v71, v158
	s_or_b64 s[40:41], s[44:45], s[2:3]
	v_add_f32_e32 v71, 1.0, v71
	v_log_f32_e32 v71, v71
	s_nop 0
	v_cndmask_b32_e64 v71, 0, -v71, s[40:41]
	v_add_f32_e32 v75, v71, v76
	s_nop 0
	v_min_f32_e32 v159, 0x42c80000, v79
	v_add_u32_e32 v76, 0x9b, v143
	v_cmp_lt_i32_e64 s[2:3], v76, v176
	v_exp_f32_e32 v76, v159
	s_or_b64 s[42:43], s[44:45], s[2:3]
	v_add_f32_e32 v76, 1.0, v76
	v_log_f32_e32 v76, v76
	s_nop 0
	v_cndmask_b32_e64 v76, 0, -v76, s[42:43]
	v_add_f32_e32 v77, v76, v75
	v_cvt_pk_bf16_f32 v75, v71, v76
	v_lshlrev_b32_e32 v78, 16, v75
	v_sub_f32_e32 v71, v71, v78
	v_and_b32_e32 v78, 0xffff0000, v75
	v_sub_f32_e32 v76, v76, v78
	v_cvt_pk_bf16_f32 v71, v71, v76
	v_add_u32_e32 v76, 0xa0, v143
	v_cmp_lt_i32_e64 s[2:3], v76, v176
	s_or_b64 s[46:47], s[44:45], s[2:3]
	v_cmp_lt_i32_e64 s[2:3], v49, v176
	v_exp_f32_e32 v49, v157
	s_or_b64 s[48:49], s[44:45], s[2:3]
	v_cndmask_b32_e64 v48, 0, -v48, s[46:47]
	v_add_f32_e32 v76, v48, v77
	v_add_f32_e32 v49, 1.0, v49
	v_log_f32_e32 v49, v49
	s_nop 0
	v_cndmask_b32_e64 v49, 0, -v49, s[48:49]
	v_cvt_pk_bf16_f32 v136, v48, v49
	v_add_f32_e32 v77, v49, v76
	v_lshlrev_b32_e32 v76, 16, v136
	v_sub_f32_e32 v48, v48, v76
	v_and_b32_e32 v76, 0xffff0000, v136
	v_sub_f32_e32 v49, v49, v76
	v_cvt_pk_bf16_f32 v76, v48, v49
	s_nop 0
	v_min_f32_e32 v160, 0x42c80000, v50
	v_add_u32_e32 v48, 0xa2, v143
	s_nop 0
	v_cmp_lt_i32_e64 s[2:3], v48, v176
	v_min_f32_e32 v161, 0x42c80000, v51
	v_add_u32_e32 v50, 0xa3, v143
	s_or_b64 s[50:51], s[44:45], s[2:3]
	v_exp_f32_e32 v48, v160
	v_cmp_lt_i32_e64 s[2:3], v50, v176
	v_exp_f32_e32 v50, v161
	s_or_b64 s[52:53], s[44:45], s[2:3]
	v_add_f32_e32 v48, 1.0, v48
	v_log_f32_e32 v48, v48
	v_add_f32_e32 v50, 1.0, v50
	v_log_f32_e32 v50, v50
	v_cndmask_b32_e64 v48, 0, -v48, s[50:51]
	v_add_f32_e32 v49, v48, v77
	v_cndmask_b32_e64 v50, 0, -v50, s[52:53]
	v_cvt_pk_bf16_f32 v137, v48, v50
	v_lshlrev_b32_e32 v51, 16, v137
	v_sub_f32_e32 v48, v48, v51
	v_and_b32_e32 v51, 0xffff0000, v137
	v_add_f32_e32 v49, v50, v49
	v_sub_f32_e32 v50, v50, v51
	v_cvt_pk_bf16_f32 v77, v48, v50
	s_nop 0
	v_min_f32_e32 v162, 0x42c80000, v52
	v_add_u32_e32 v48, 0xa8, v143
	s_nop 0
	v_cmp_lt_i32_e64 s[2:3], v48, v176
	v_min_f32_e32 v163, 0x42c80000, v53
	v_add_u32_e32 v50, 0xa9, v143
	s_or_b64 s[54:55], s[44:45], s[2:3]
	v_exp_f32_e32 v48, v162
	v_cmp_lt_i32_e64 s[2:3], v50, v176
	v_exp_f32_e32 v50, v163
	s_or_b64 s[56:57], s[44:45], s[2:3]
	v_add_f32_e32 v48, 1.0, v48
	v_log_f32_e32 v48, v48
	v_add_f32_e32 v50, 1.0, v50
	v_log_f32_e32 v50, v50
	v_pk_add_f32 v[52:53], v[152:153], v[88:89] op_sel_hi:[0,1]
	v_cndmask_b32_e64 v48, 0, -v48, s[54:55]
	v_add_f32_e32 v49, v48, v49
	v_cndmask_b32_e64 v50, 0, -v50, s[56:57]
	v_cvt_pk_bf16_f32 v138, v48, v50
	v_lshlrev_b32_e32 v51, 16, v138
	v_sub_f32_e32 v48, v48, v51
	v_and_b32_e32 v51, 0xffff0000, v138
	v_add_f32_e32 v49, v50, v49
	v_sub_f32_e32 v50, v50, v51
	v_cvt_pk_bf16_f32 v78, v48, v50
	s_nop 0
	v_min_f32_e32 v164, 0x42c80000, v54
	v_add_u32_e32 v48, 0xaa, v143
	s_nop 0
	v_cmp_lt_i32_e64 s[2:3], v48, v176
	v_min_f32_e32 v165, 0x42c80000, v55
	v_add_u32_e32 v50, 0xab, v143
	s_or_b64 s[58:59], s[44:45], s[2:3]
	v_exp_f32_e32 v48, v164
	v_cmp_lt_i32_e64 s[2:3], v50, v176
	v_exp_f32_e32 v50, v165
	s_or_b64 s[60:61], s[44:45], s[2:3]
	v_add_f32_e32 v48, 1.0, v48
	v_log_f32_e32 v48, v48
	v_add_f32_e32 v50, 1.0, v50
	v_log_f32_e32 v50, v50
	v_pk_add_f32 v[54:55], v[152:153], v[90:91] op_sel_hi:[0,1]
	v_cndmask_b32_e64 v48, 0, -v48, s[58:59]
	v_add_f32_e32 v49, v48, v49
	v_cndmask_b32_e64 v50, 0, -v50, s[60:61]
	v_cvt_pk_bf16_f32 v139, v48, v50
	v_lshlrev_b32_e32 v51, 16, v139
	v_sub_f32_e32 v48, v48, v51
	v_and_b32_e32 v51, 0xffff0000, v139
	v_add_f32_e32 v49, v50, v49
	v_sub_f32_e32 v50, v50, v51
	v_cvt_pk_bf16_f32 v79, v48, v50
	s_nop 0
	v_min_f32_e32 v166, 0x42c80000, v56
	v_add_u32_e32 v48, 0xb0, v143
	s_nop 0
	v_cmp_lt_i32_e64 s[2:3], v48, v176
	v_min_f32_e32 v167, 0x42c80000, v57
	v_add_u32_e32 v50, 0xb1, v143
	s_or_b64 s[62:63], s[44:45], s[2:3]
	v_exp_f32_e32 v48, v166
	v_cmp_lt_i32_e64 s[2:3], v50, v176
	v_exp_f32_e32 v50, v167
	s_or_b64 s[64:65], s[44:45], s[2:3]
	v_add_f32_e32 v48, 1.0, v48
	v_log_f32_e32 v48, v48
	v_add_f32_e32 v50, 1.0, v50
	v_log_f32_e32 v50, v50
	v_pk_add_f32 v[56:57], v[152:153], v[92:93] op_sel_hi:[0,1]
	v_cndmask_b32_e64 v48, 0, -v48, s[62:63]
	v_add_f32_e32 v49, v48, v49
	v_cndmask_b32_e64 v50, 0, -v50, s[64:65]
; #define MFMA32(a, b, c) __builtin_amdgcn_mfma_f32_32x32x16_bf16((a), (b), (c), 0, 0, 0)
; DI unsigned pk_bf16(float lo, float hi) { f32x2 v = {lo, hi}; bf2_t b = __builtin_convertvector(v, bf2_t); return __builtin_bit_cast(unsigned, b); }
; DI int crow(int i, int h) { return (i & 3) + 8 * (i >> 2) + 4 * h; }
; DI float fast_exp2(float x) { return __builtin_amdgcn_exp2f(x); }
; template <int DQK, bool SB, bool SMAX>
; DI void attn_item(const Params& p, char* smem, int bh, int qb, float Mb) {
;     ...
;         tsum += other_half(tsum);
; #pragma unroll
;         for (int s = 0; s < 2; ++s) {
;           ca[0] = MFMA32(tri[s], hi[s], ca[0]);
;           ca[0] = MFMA32(tri[s], lo[s], ca[0]);
;           ca[0] = MFMA32(ones, hi[2 + s], ca[0]);
;           ca[0] = MFMA32(ones, lo[2 + s], ca[0]);
;           ca[1] = MFMA32(tri[s], hi[2 + s], ca[1]);
;           ca[1] = MFMA32(tri[s], lo[2 + s], ca[1]);
;         }
; #pragma unroll
;         for (int kb = 0; kb < 2; ++kb)
; #pragma unroll
;           for (int i = 0; i < 16; ++i) {
;             const int key = kb0 + kb * 32 + crow(i, h);
;             const bool valid = !diag || (key < query);
;             st[kb][i] = valid ? fast_exp2(ca[kb][i]) : 0.f;
;           }
;         carry += tsum;
;     ...
; #pragma unroll
;           for (int e = 0; e < 4; ++e) w[e] = pk_bf16(st[kb][8 * s + 2 * e], st[kb][8 * s + 2 * e + 1]);
;           pk[kb * 2 + s] = __builtin_bit_cast(bf16x8, w);
;         }
; #pragma unroll
;       for (int kk = 0; kk < 4; ++kk)
; #pragma unroll
;         for (int db = 0; db < 2; ++db) {
;           const s16x4 v0 = __builtin_amdgcn_ds_read_tr16_b64_v4i16((lds_s16x4*)(vc + voff + (16 * kk) * VSTR + 32 * db));
;           const s16x4 v1 = __builtin_amdgcn_ds_read_tr16_b64_v4i16((lds_s16x4*)(vc + voff + (16 * kk + 8) * VSTR + 32 * db));
;           const bf16x8 vf = __builtin_shufflevector(v0, v1, 0, 1, 2, 3, 4, 5, 6, 7);
;           O[db] = MFMA32(vf, pk[kk], O[db]);
	v_cvt_pk_bf16_f32 v140, v48, v50
	v_lshlrev_b32_e32 v51, 16, v140
	v_sub_f32_e32 v48, v48, v51
	v_and_b32_e32 v51, 0xffff0000, v140
	v_add_f32_e32 v49, v50, v49
	v_sub_f32_e32 v50, v50, v51
	v_cvt_pk_bf16_f32 v144, v48, v50
	s_nop 0
	v_min_f32_e32 v168, 0x42c80000, v58
	v_add_u32_e32 v48, 0xb2, v143
	s_nop 0
	v_cmp_lt_i32_e64 s[2:3], v48, v176
	v_min_f32_e32 v169, 0x42c80000, v59
	v_add_u32_e32 v50, 0xb3, v143
	s_or_b64 s[66:67], s[44:45], s[2:3]
	v_exp_f32_e32 v48, v168
	v_cmp_lt_i32_e64 s[2:3], v50, v176
	v_exp_f32_e32 v50, v169
	s_or_b64 s[68:69], s[44:45], s[2:3]
	v_add_f32_e32 v48, 1.0, v48
	v_log_f32_e32 v48, v48
	v_add_f32_e32 v50, 1.0, v50
	v_log_f32_e32 v50, v50
	v_pk_add_f32 v[58:59], v[152:153], v[94:95] op_sel_hi:[0,1]
	v_cndmask_b32_e64 v48, 0, -v48, s[66:67]
	v_add_f32_e32 v49, v48, v49
	v_cndmask_b32_e64 v50, 0, -v50, s[68:69]
	v_cvt_pk_bf16_f32 v141, v48, v50
	v_lshlrev_b32_e32 v51, 16, v141
	v_sub_f32_e32 v48, v48, v51
	v_and_b32_e32 v51, 0xffff0000, v141
	v_add_f32_e32 v49, v50, v49
	v_sub_f32_e32 v50, v50, v51
	v_cvt_pk_bf16_f32 v145, v48, v50
	s_nop 0
	v_min_f32_e32 v170, 0x42c80000, v60
	v_add_u32_e32 v48, 0xb8, v143
	s_nop 0
	v_cmp_lt_i32_e64 s[2:3], v48, v176
	v_min_f32_e32 v171, 0x42c80000, v61
	v_add_u32_e32 v50, 0xb9, v143
	s_or_b64 s[70:71], s[44:45], s[2:3]
	v_exp_f32_e32 v48, v170
	v_cmp_lt_i32_e64 s[2:3], v50, v176
	v_exp_f32_e32 v50, v171
	s_or_b64 s[72:73], s[44:45], s[2:3]
	v_add_f32_e32 v48, 1.0, v48
	v_log_f32_e32 v48, v48
	v_add_f32_e32 v50, 1.0, v50
	v_log_f32_e32 v50, v50
	v_pk_add_f32 v[60:61], v[152:153], v[154:155] op_sel_hi:[0,1]
	v_cndmask_b32_e64 v48, 0, -v48, s[70:71]
	v_add_f32_e32 v49, v48, v49
	v_cndmask_b32_e64 v50, 0, -v50, s[72:73]
	v_cvt_pk_bf16_f32 v142, v48, v50
	v_lshlrev_b32_e32 v51, 16, v142
	v_sub_f32_e32 v48, v48, v51
	v_and_b32_e32 v51, 0xffff0000, v142
	v_add_f32_e32 v49, v50, v49
	v_sub_f32_e32 v50, v50, v51
	v_cvt_pk_bf16_f32 v146, v48, v50
	s_nop 0
	v_min_f32_e32 v182, 0x42c80000, v62
	v_add_u32_e32 v48, 0xba, v143
	s_nop 0
	v_cmp_lt_i32_e64 s[2:3], v48, v176
	v_min_f32_e32 v183, 0x42c80000, v63
	v_add_u32_e32 v50, 0xbb, v143
	s_or_b64 s[74:75], s[44:45], s[2:3]
	v_exp_f32_e32 v48, v182
	v_cmp_lt_i32_e64 s[2:3], v50, v176
	v_exp_f32_e32 v50, v183
	s_or_b64 s[44:45], s[44:45], s[2:3]
	v_add_f32_e32 v48, 1.0, v48
	v_log_f32_e32 v48, v48
	v_add_f32_e32 v50, 1.0, v50
	v_log_f32_e32 v50, v50
	v_pk_add_f32 v[62:63], v[152:153], v[158:159] op_sel_hi:[0,1]
	v_cndmask_b32_e64 v48, 0, -v48, s[74:75]
	v_add_f32_e32 v49, v48, v49
	v_cndmask_b32_e64 v50, 0, -v50, s[44:45]
	v_cvt_pk_bf16_f32 v143, v48, v50
	v_add_f32_e32 v184, v50, v49
	v_lshlrev_b32_e32 v49, 16, v143
	v_sub_f32_e32 v48, v48, v49
	v_and_b32_e32 v49, 0xffff0000, v143
	v_sub_f32_e32 v49, v50, v49
	v_cvt_pk_bf16_f32 v147, v48, v49
	v_mov_b32_e32 v48, v184
	v_mov_b32_e32 v49, v184
	s_nop 1
	v_permlane32_swap_b32_e32 v48, v49
	v_cndmask_b32_e64 v185, v48, v49, s[8:9]
	v_pk_add_f32 v[50:51], v[152:153], v[86:87] op_sel_hi:[0,1]
	v_pk_add_f32 v[48:49], v[152:153], v[84:85] op_sel_hi:[0,1]
	v_pk_add_f32 v[94:95], v[152:153], v[182:183] op_sel_hi:[0,1]
	v_pk_add_f32 v[92:93], v[152:153], v[170:171] op_sel_hi:[0,1]
	v_mfma_f32_32x32x16_bf16 v[48:63], v[96:99], v[80:83], v[48:63]
	v_add_f32_e64 v90, v152, v168
	v_add_f32_e64 v91, v152, v169
	v_add_f32_e64 v88, v152, v166
	v_add_f32_e64 v89, v152, v167
	v_add_f32_e64 v86, v152, v164
	v_add_f32_e64 v87, v152, v165
	v_pk_add_f32 v[84:85], v[152:153], v[162:163] op_sel_hi:[0,1]
	v_pk_add_f32 v[82:83], v[152:153], v[160:161] op_sel_hi:[0,1]
	v_pk_add_f32 v[80:81], v[152:153], v[156:157] op_sel_hi:[0,1]
	v_mfma_f32_32x32x16_bf16 v[48:63], v[96:99], v[64:67], v[48:63]
	v_mov_b64_e32 v[64:65], s[96:97]
	v_mov_b64_e32 v[66:67], s[98:99]
	s_nop 1
	v_mfma_f32_32x32x16_bf16 v[48:63], v[64:67], v[136:139], v[48:63]
	v_mfma_f32_32x32x16_bf16 v[48:63], v[64:67], v[76:79], v[48:63]
	v_mfma_f32_32x32x16_bf16 v[48:63], v[100:103], v[72:75], v[48:63]
	v_mfma_f32_32x32x16_bf16 v[48:63], v[100:103], v[68:71], v[48:63]
	v_mfma_f32_32x32x16_bf16 v[48:63], v[64:67], v[140:143], v[48:63]
	v_mfma_f32_32x32x16_bf16 v[48:63], v[64:67], v[144:147], v[48:63]
	v_mfma_f32_32x32x16_bf16 v[80:95], v[96:99], v[136:139], v[80:95]
	s_nop 10
	v_exp_f32_e32 v48, v48
	s_nop 0
	v_cndmask_b32_e32 v64, 0, v48, vcc
	v_exp_f32_e32 v48, v49
	v_mfma_f32_32x32x16_bf16 v[80:95], v[96:99], v[76:79], v[80:95]
	v_cndmask_b32_e64 v65, 0, v48, s[12:13]
	v_exp_f32_e32 v48, v50
	s_nop 0
	v_cndmask_b32_e64 v66, 0, v48, s[14:15]
	v_exp_f32_e32 v48, v51
	v_mfma_f32_32x32x16_bf16 v[80:95], v[100:103], v[140:143], v[80:95]
	v_add_u32_e32 v141, v198, v200
	ds_read_b64_tr_b16 v[136:137], v141 offset:18432
	ds_read_b64_tr_b16 v[138:139], v141 offset:19584
	v_cndmask_b32_e64 v67, 0, v48, s[16:17]
	v_exp_f32_e32 v48, v52
	v_add_f32_e32 v140, v184, v185
	v_add_f32_e32 v152, v152, v140
	v_cndmask_b32_e64 v68, 0, v48, s[18:19]
	v_exp_f32_e32 v48, v53
	v_mfma_f32_32x32x16_bf16 v[80:95], v[100:103], v[144:147], v[80:95]
	v_cndmask_b32_e64 v69, 0, v48, s[20:21]
	v_exp_f32_e32 v48, v54
	s_nop 0
	v_cndmask_b32_e64 v70, 0, v48, s[22:23]
	v_exp_f32_e32 v48, v55
	s_nop 6
	v_exp_f32_e32 v49, v81
	v_exp_f32_e32 v50, v82
	v_exp_f32_e32 v51, v83
	v_cndmask_b32_e64 v71, 0, v48, s[24:25]
	v_exp_f32_e32 v48, v56
	v_exp_f32_e32 v56, v88
	v_exp_f32_e32 v52, v84
	v_exp_f32_e32 v53, v85
	v_cndmask_b32_e64 v72, 0, v48, s[26:27]
	v_exp_f32_e32 v48, v57
	v_exp_f32_e32 v57, v89
	v_exp_f32_e32 v54, v86
	v_exp_f32_e32 v55, v87
	v_cndmask_b32_e64 v73, 0, v48, s[28:29]
	v_exp_f32_e32 v48, v58
	v_exp_f32_e32 v58, v90
	v_cvt_pk_bf16_f32 v88, v72, v73
	v_cndmask_b32_e64 v49, 0, v49, s[48:49]
	v_cndmask_b32_e64 v74, 0, v48, s[30:31]
	v_exp_f32_e32 v48, v59
	v_exp_f32_e32 v59, v91
	v_cndmask_b32_e64 v50, 0, v50, s[50:51]
	v_cndmask_b32_e64 v51, 0, v51, s[52:53]
	v_cndmask_b32_e64 v75, 0, v48, s[34:35]
	v_exp_f32_e32 v48, v60
	v_exp_f32_e32 v60, v92
	v_cvt_pk_bf16_f32 v92, v64, v65
	v_cvt_pk_bf16_f32 v89, v74, v75
	v_cndmask_b32_e64 v76, 0, v48, s[36:37]
	v_exp_f32_e32 v48, v61
	v_exp_f32_e32 v61, v93
	v_cvt_pk_bf16_f32 v93, v66, v67
	v_cndmask_b32_e64 v52, 0, v52, s[54:55]
	v_cndmask_b32_e64 v77, 0, v48, s[38:39]
	v_exp_f32_e32 v48, v62
	v_exp_f32_e32 v62, v94
	v_cvt_pk_bf16_f32 v94, v68, v69
	v_cvt_pk_bf16_f32 v90, v76, v77
	v_cndmask_b32_e64 v78, 0, v48, s[40:41]
	v_exp_f32_e32 v48, v63
	v_exp_f32_e32 v63, v95
	v_cvt_pk_bf16_f32 v95, v70, v71
	v_cndmask_b32_e64 v53, 0, v53, s[56:57]
	v_cndmask_b32_e64 v79, 0, v48, s[42:43]
	s_waitcnt lgkmcnt(0)
; #define MFMA32(a, b, c) __builtin_amdgcn_mfma_f32_32x32x16_bf16((a), (b), (c), 0, 0, 0)
; DI unsigned pk_bf16(float lo, float hi) { f32x2 v = {lo, hi}; bf2_t b = __builtin_convertvector(v, bf2_t); return __builtin_bit_cast(unsigned, b); }
; template <int DQK, bool SB, bool SMAX>
; DI void attn_item(const Params& p, char* smem, int bh, int qb, float Mb) {
;     ...
; #pragma unroll
;           for (int e = 0; e < 4; ++e) w[e] = pk_bf16(st[kb][8 * s + 2 * e], st[kb][8 * s + 2 * e + 1]);
;           pk[kb * 2 + s] = __builtin_bit_cast(bf16x8, w);
;         }
; #pragma unroll
;       for (int kk = 0; kk < 4; ++kk)
; #pragma unroll
;         for (int db = 0; db < 2; ++db) {
;           const s16x4 v0 = __builtin_amdgcn_ds_read_tr16_b64_v4i16((lds_s16x4*)(vc + voff + (16 * kk) * VSTR + 32 * db));
;           const s16x4 v1 = __builtin_amdgcn_ds_read_tr16_b64_v4i16((lds_s16x4*)(vc + voff + (16 * kk + 8) * VSTR + 32 * db));
;           const bf16x8 vf = __builtin_shufflevector(v0, v1, 0, 1, 2, 3, 4, 5, 6, 7);
;           O[db] = MFMA32(vf, pk[kk], O[db]);
;         }
	v_mfma_f32_32x32x16_bf16 v[32:47], v[136:139], v[92:95], v[32:47]
	ds_read_b64_tr_b16 v[136:137], v141 offset:18496
	ds_read_b64_tr_b16 v[138:139], v141 offset:19648
	v_cvt_pk_bf16_f32 v91, v78, v79
	v_exp_f32_e32 v48, v80
	v_cndmask_b32_e64 v54, 0, v54, s[58:59]
	v_cndmask_b32_e64 v55, 0, v55, s[60:61]
	v_cvt_pk_bf16_f32 v85, v50, v51
	v_cndmask_b32_e64 v48, 0, v48, s[46:47]
	s_waitcnt lgkmcnt(0)
	v_mfma_f32_32x32x16_bf16 v[16:31], v[136:139], v[92:95], v[16:31]
	ds_read_b64_tr_b16 v[92:93], v141 offset:20736
	ds_read_b64_tr_b16 v[94:95], v141 offset:21888
	v_cvt_pk_bf16_f32 v84, v48, v49
	v_cvt_pk_bf16_f32 v86, v52, v53
	v_cvt_pk_bf16_f32 v87, v54, v55
	v_cndmask_b32_e64 v56, 0, v56, s[62:63]
	v_cndmask_b32_e64 v57, 0, v57, s[64:65]
	v_cndmask_b32_e64 v58, 0, v58, s[66:67]
	s_waitcnt lgkmcnt(0)
	v_mfma_f32_32x32x16_bf16 v[32:47], v[92:95], v[88:91], v[32:47]
	ds_read_b64_tr_b16 v[92:93], v141 offset:20800
	ds_read_b64_tr_b16 v[94:95], v141 offset:21952
	v_cndmask_b32_e64 v59, 0, v59, s[68:69]
	v_cndmask_b32_e64 v60, 0, v60, s[70:71]
	v_cndmask_b32_e64 v61, 0, v61, s[72:73]
	v_cndmask_b32_e64 v62, 0, v62, s[74:75]
	v_cndmask_b32_e64 v63, 0, v63, s[44:45]
	v_cvt_pk_bf16_f32 v80, v56, v57
	s_waitcnt lgkmcnt(0)
	v_mfma_f32_32x32x16_bf16 v[16:31], v[92:95], v[88:91], v[16:31]
	ds_read_b64_tr_b16 v[88:89], v141 offset:23040
	ds_read_b64_tr_b16 v[90:91], v141 offset:24192
	v_cvt_pk_bf16_f32 v81, v58, v59
	v_cvt_pk_bf16_f32 v82, v60, v61
	v_cvt_pk_bf16_f32 v83, v62, v63
	s_waitcnt lgkmcnt(0)
	v_mfma_f32_32x32x16_bf16 v[32:47], v[88:91], v[84:87], v[32:47]
	ds_read_b64_tr_b16 v[88:89], v141 offset:23104
	ds_read_b64_tr_b16 v[90:91], v141 offset:24256
	s_waitcnt lgkmcnt(0)
	v_mfma_f32_32x32x16_bf16 v[16:31], v[88:91], v[84:87], v[16:31]
	ds_read_b64_tr_b16 v[84:85], v141 offset:25344
	ds_read_b64_tr_b16 v[86:87], v141 offset:26496
	s_waitcnt lgkmcnt(0)
	v_mfma_f32_32x32x16_bf16 v[32:47], v[84:87], v[80:83], v[32:47]
	ds_read_b64_tr_b16 v[84:85], v141 offset:25408
	ds_read_b64_tr_b16 v[86:87], v141 offset:26560
	s_waitcnt lgkmcnt(0)
	v_mfma_f32_32x32x16_bf16 v[16:31], v[84:87], v[80:83], v[16:31]

; DI unsigned pk_bf16(float lo, float hi) { f32x2 v = {lo, hi}; bf2_t b = __builtin_convertvector(v, bf2_t); return __builtin_bit_cast(unsigned, b); }
; DI float bf_lo(unsigned u) { return __uint_as_float(u << 16); }
; DI float bf_hi(unsigned u) { return __uint_as_float(u & 0xffff0000u); }
; DI int crow(int i, int h) { return (i & 3) + 8 * (i >> 2) + 4 * h; }
; DI float fast_exp2(float x) { return __builtin_amdgcn_exp2f(x); }
; DI float fast_log2(float x) { return __builtin_amdgcn_logf(x); }
; #define AT_LOAD(SET, IT) { const int kl_ = AT_KB(IT); \
;     _Pragma("unroll") for (int i = 0; i < KPT; ++i) kreg[SET][i] = *(const u32x4*)(Kg + (size_t)kl_ * DQK + (tid + 256 * i) * 8); \
;     _Pragma("unroll") for (int i = 0; i < 2; ++i) vreg[SET][i] = *(const u32x4*)(Vg + (size_t)kl_ * 64 + (tid + 256 * i) * 8); \
;     __builtin_amdgcn_sched_barrier(0); }
; template <int DQK, bool SB, bool SMAX>
; DI void attn_item(const Params& p, char* smem, int bh, int qb, float Mb) {
;     ...
;     AT_WRITE(0, st2 ^ 1)
;     AT_LOAD(0, (it + 2 < nt) ? it + 2 : nt - 1)
;     if (active) {
;       const bool diag = (kb0 + 64 > qw0);
;       bf16x8 pk[4];
;     ...
;           for (int i2 = 0; i2 < 8; ++i2) {
;             float lk[2];
; #pragma unroll
;             for (int e = 0; e < 2; ++e) {
;               const int i = 2 * i2 + e;
;               const float z = fminf(st[kb][i], 100.f);
;               const int key = kb0 + kb * 32 + crow(i, h);
;               const bool valid = !diag || (key < query);
;               float l = -fast_log2(1.f + fast_exp2(z));
;               l = valid ? l : 0.f;
;               lk[e] = l;
;               tsum += l;
;               ca[kb][i] = z + carry;
;             }
;             const unsigned hp = pk_bf16(lk[0], lk[1]);
;             const unsigned lp = pk_bf16(lk[0] - bf_lo(hp), lk[1] - bf_hi(hp));
;             const int kk = kb * 2 + (i2 >> 2), w = i2 & 3;
;             hi[kk][2 * w] = (short)(hp & 0xffffu); hi[kk][2 * w + 1] = (short)(hp >> 16);
;             lo[kk][2 * w] = (short)(lp & 0xffffu); lo[kk][2 * w + 1] = (short)(lp >> 16);
;           }
.LBB0_442:
	s_or_b64 exec, exec, s[2:3]
	s_add_i32 s2, s4, 1
	s_xor_b32 s3, s4, 0x3fffffe
	s_add_i32 s3, s3, s1
	s_lshl_b32 s3, s3, 6
	s_cmp_lt_u32 s2, s1
	s_cselect_b32 s2, s3, 0
	s_ashr_i32 s3, s2, 31
	s_lshl_b64 s[2:3], s[2:3], 7
	v_lshl_add_u64 v[80:81], v[148:149], 0, s[2:3]
	s_waitcnt vmcnt(3)
	ds_write_b128 v203, v[120:123]
	s_waitcnt vmcnt(2)
	ds_write_b128 v204, v[124:127]
	s_waitcnt vmcnt(1)
	ds_write_b128 v203, v[128:131] offset:18432
	s_waitcnt vmcnt(0)
	ds_write_b128 v204, v[132:135] offset:18432
	v_add_co_u32_e32 v82, vcc, s7, v80
	s_nop 1
	v_addc_co_u32_e32 v83, vcc, 0, v81, vcc
	global_load_dwordx4 v[120:123], v[80:81], off
	global_load_dwordx4 v[124:127], v[82:83], off
	v_lshl_add_u64 v[80:81], v[150:151], 0, s[2:3]
	v_add_co_u32_e32 v82, vcc, 0x1000, v80
	s_nop 1
	v_addc_co_u32_e32 v83, vcc, 0, v81, vcc
	global_load_dwordx4 v[128:131], v[80:81], off
	global_load_dwordx4 v[132:135], v[82:83], off
	s_and_saveexec_b64 s[80:81], s[12:13]
	s_cbranch_execz .LBB0_444
	s_nop 0
	v_add_u32_e32 v143, s78, v197
	v_min_f32_e32 v84, 0x42c80000, v64
	s_nop 0
	v_exp_f32_e32 v64, v84
	v_min_f32_e32 v85, 0x42c80000, v65
	v_add_u32_e32 v65, 0x41, v143
	v_cmp_lt_i32_e64 s[2:3], v65, v176
	v_exp_f32_e32 v65, v85
	v_add_f32_e32 v64, 1.0, v64
	v_log_f32_e32 v64, v64
	v_add_u32_e32 v80, 64, v143
	v_add_f32_e32 v65, 1.0, v65
	v_log_f32_e32 v65, v65
	v_cmp_le_i32_e64 s[44:45], s14, v181
	v_cmp_lt_i32_e32 vcc, v80, v176
	s_or_b64 vcc, s[44:45], vcc
	s_or_b64 s[12:13], s[44:45], s[2:3]
	v_cndmask_b32_e64 v64, 0, -v64, vcc
	v_add_f32_e32 v80, 0, v64
	v_cndmask_b32_e64 v65, 0, -v65, s[12:13]
	v_add_f32_e32 v81, v65, v80
	v_cvt_pk_bf16_f32 v80, v64, v65
	v_lshlrev_b32_e32 v82, 16, v80
	v_sub_f32_e32 v64, v64, v82
	v_and_b32_e32 v82, 0xffff0000, v80
	v_sub_f32_e32 v65, v65, v82
	v_cvt_pk_bf16_f32 v64, v64, v65
	s_nop 0
	v_min_f32_e32 v86, 0x42c80000, v66
	v_add_u32_e32 v65, 0x42, v143
	s_nop 0
	v_cmp_lt_i32_e64 s[2:3], v65, v176
	v_min_f32_e32 v87, 0x42c80000, v67
	v_add_u32_e32 v67, 0x43, v143
	s_or_b64 s[14:15], s[44:45], s[2:3]
	v_exp_f32_e32 v65, v86
	v_cmp_lt_i32_e64 s[2:3], v67, v176
	v_exp_f32_e32 v67, v87
	s_or_b64 s[16:17], s[44:45], s[2:3]
	v_add_f32_e32 v65, 1.0, v65
	v_log_f32_e32 v65, v65
	v_add_f32_e32 v67, 1.0, v67
	v_log_f32_e32 v67, v67
	s_nop 0
	v_cndmask_b32_e64 v65, 0, -v65, s[14:15]
	v_add_f32_e32 v66, v65, v81
	v_cndmask_b32_e64 v67, 0, -v67, s[16:17]
	v_cvt_pk_bf16_f32 v81, v65, v67
	v_lshlrev_b32_e32 v82, 16, v81
	v_sub_f32_e32 v65, v65, v82
	v_and_b32_e32 v82, 0xffff0000, v81
	v_add_f32_e32 v66, v67, v66
	v_sub_f32_e32 v67, v67, v82
	v_cvt_pk_bf16_f32 v65, v65, v67
	s_nop 0
	v_min_f32_e32 v88, 0x42c80000, v68
	v_add_u32_e32 v67, 0x48, v143
	s_nop 0
	v_cmp_lt_i32_e64 s[2:3], v67, v176
	v_min_f32_e32 v89, 0x42c80000, v69
	v_add_u32_e32 v68, 0x49, v143
	s_or_b64 s[18:19], s[44:45], s[2:3]
	v_exp_f32_e32 v67, v88
	v_cmp_lt_i32_e64 s[2:3], v68, v176
	v_exp_f32_e32 v68, v89
	s_or_b64 s[20:21], s[44:45], s[2:3]
	v_add_f32_e32 v67, 1.0, v67
	v_log_f32_e32 v67, v67
	v_add_f32_e32 v68, 1.0, v68
	v_log_f32_e32 v68, v68
	s_nop 0
	v_cndmask_b32_e64 v67, 0, -v67, s[18:19]
	v_add_f32_e32 v66, v67, v66
	v_cndmask_b32_e64 v68, 0, -v68, s[20:21]
	v_cvt_pk_bf16_f32 v82, v67, v68
	v_add_f32_e32 v69, v68, v66
	v_lshlrev_b32_e32 v66, 16, v82
	v_sub_f32_e32 v66, v67, v66
	v_and_b32_e32 v67, 0xffff0000, v82
	v_sub_f32_e32 v67, v68, v67
	v_cvt_pk_bf16_f32 v66, v66, v67
	s_nop 0
	v_min_f32_e32 v90, 0x42c80000, v70
	v_add_u32_e32 v67, 0x4a, v143
	v_cmp_lt_i32_e64 s[2:3], v67, v176
	v_exp_f32_e32 v67, v90
	s_or_b64 s[22:23], s[44:45], s[2:3]
	v_min_f32_e32 v156, 0x42c80000, v48
	v_min_f32_e32 v157, 0x42c80000, v49
	v_add_f32_e32 v67, 1.0, v67
	v_log_f32_e32 v67, v67
	v_add_u32_e32 v49, 0x61, v143
	v_exp_f32_e32 v48, v156
	s_mov_b32 s97, s96
	v_cndmask_b32_e64 v67, 0, -v67, s[22:23]
	v_add_f32_e32 v68, v67, v69
	s_nop 0
	v_min_f32_e32 v91, 0x42c80000, v71
	v_add_u32_e32 v69, 0x4b, v143
	v_cmp_lt_i32_e64 s[2:3], v69, v176
	v_exp_f32_e32 v69, v91
	s_or_b64 s[24:25], s[44:45], s[2:3]
	v_add_f32_e32 v48, 1.0, v48
	v_log_f32_e32 v48, v48
	v_add_f32_e32 v69, 1.0, v69
	v_log_f32_e32 v69, v69
	s_mov_b32 s98, s96
	s_mov_b32 s99, s96
	v_cndmask_b32_e64 v69, 0, -v69, s[24:25]
	v_cvt_pk_bf16_f32 v83, v67, v69
	v_lshlrev_b32_e32 v70, 16, v83
	v_sub_f32_e32 v67, v67, v70
	v_and_b32_e32 v70, 0xffff0000, v83
	v_add_f32_e32 v68, v69, v68
	v_sub_f32_e32 v69, v69, v70
	v_cvt_pk_bf16_f32 v67, v67, v69
	s_nop 0
	v_min_f32_e32 v92, 0x42c80000, v72
	v_add_u32_e32 v69, 0x50, v143
	s_nop 0
	v_cmp_lt_i32_e64 s[2:3], v69, v176
	v_min_f32_e32 v93, 0x42c80000, v73
	v_add_u32_e32 v70, 0x51, v143
	s_or_b64 s[26:27], s[44:45], s[2:3]
	v_exp_f32_e32 v69, v92
	v_cmp_lt_i32_e64 s[2:3], v70, v176
	v_exp_f32_e32 v70, v93
	s_or_b64 s[28:29], s[44:45], s[2:3]
	v_add_f32_e32 v69, 1.0, v69
	v_log_f32_e32 v69, v69
	v_add_f32_e32 v70, 1.0, v70
	v_log_f32_e32 v70, v70
	v_cndmask_b32_e64 v69, 0, -v69, s[26:27]
	v_add_f32_e32 v68, v69, v68
	v_cndmask_b32_e64 v70, 0, -v70, s[28:29]
	v_cvt_pk_bf16_f32 v72, v69, v70
	v_add_f32_e32 v71, v70, v68
	v_lshlrev_b32_e32 v68, 16, v72
	v_sub_f32_e32 v68, v69, v68
	v_and_b32_e32 v69, 0xffff0000, v72
	v_sub_f32_e32 v69, v70, v69
	v_cvt_pk_bf16_f32 v68, v68, v69
	s_nop 0
	v_min_f32_e32 v94, 0x42c80000, v74
	v_add_u32_e32 v69, 0x52, v143
	v_cmp_lt_i32_e64 s[2:3], v69, v176
	v_exp_f32_e32 v69, v94
	s_or_b64 s[30:31], s[44:45], s[2:3]
	v_add_f32_e32 v69, 1.0, v69
	v_log_f32_e32 v69, v69
	s_nop 0
	v_cndmask_b32_e64 v69, 0, -v69, s[30:31]
	v_add_f32_e32 v70, v69, v71
	s_nop 0
	v_min_f32_e32 v95, 0x42c80000, v75
	v_add_u32_e32 v71, 0x53, v143
	v_cmp_lt_i32_e64 s[2:3], v71, v176
; DI unsigned pk_bf16(float lo, float hi) { f32x2 v = {lo, hi}; bf2_t b = __builtin_convertvector(v, bf2_t); return __builtin_bit_cast(unsigned, b); }
; DI float bf_lo(unsigned u) { return __uint_as_float(u << 16); }
; DI float bf_hi(unsigned u) { return __uint_as_float(u & 0xffff0000u); }
; DI int crow(int i, int h) { return (i & 3) + 8 * (i >> 2) + 4 * h; }
; DI float fast_exp2(float x) { return __builtin_amdgcn_exp2f(x); }
; DI float fast_log2(float x) { return __builtin_amdgcn_logf(x); }
; template <int DQK, bool SB, bool SMAX>
; DI void attn_item(const Params& p, char* smem, int bh, int qb, float Mb) {
;     ...
;           for (int i2 = 0; i2 < 8; ++i2) {
;             float lk[2];
; #pragma unroll
;             for (int e = 0; e < 2; ++e) {
;               const int i = 2 * i2 + e;
;               const float z = fminf(st[kb][i], 100.f);
;               const int key = kb0 + kb * 32 + crow(i, h);
;               const bool valid = !diag || (key < query);
;               float l = -fast_log2(1.f + fast_exp2(z));
;               l = valid ? l : 0.f;
;               lk[e] = l;
;               tsum += l;
;               ca[kb][i] = z + carry;
;             }
;             const unsigned hp = pk_bf16(lk[0], lk[1]);
;             const unsigned lp = pk_bf16(lk[0] - bf_lo(hp), lk[1] - bf_hi(hp));
;             const int kk = kb * 2 + (i2 >> 2), w = i2 & 3;
;             hi[kk][2 * w] = (short)(hp & 0xffffu); hi[kk][2 * w + 1] = (short)(hp >> 16);
;             lo[kk][2 * w] = (short)(lp & 0xffffu); lo[kk][2 * w + 1] = (short)(lp >> 16);
;           }
	v_exp_f32_e32 v71, v95
	s_or_b64 s[34:35], s[44:45], s[2:3]
	v_add_f32_e32 v71, 1.0, v71
	v_log_f32_e32 v71, v71
	s_nop 0
	v_cndmask_b32_e64 v71, 0, -v71, s[34:35]
	v_cvt_pk_bf16_f32 v73, v69, v71
	v_lshlrev_b32_e32 v74, 16, v73
	v_sub_f32_e32 v69, v69, v74
	v_and_b32_e32 v74, 0xffff0000, v73
	v_add_f32_e32 v70, v71, v70
	v_sub_f32_e32 v71, v71, v74
	v_cvt_pk_bf16_f32 v69, v69, v71
	s_nop 0
	v_min_f32_e32 v154, 0x42c80000, v76
	v_add_u32_e32 v71, 0x58, v143
	s_nop 0
	v_cmp_lt_i32_e64 s[2:3], v71, v176
	v_min_f32_e32 v155, 0x42c80000, v77
	v_add_u32_e32 v74, 0x59, v143
	s_or_b64 s[36:37], s[44:45], s[2:3]
	v_exp_f32_e32 v71, v154
	v_cmp_lt_i32_e64 s[2:3], v74, v176
	v_exp_f32_e32 v74, v155
	s_or_b64 s[38:39], s[44:45], s[2:3]
	v_add_f32_e32 v71, 1.0, v71
	v_log_f32_e32 v71, v71
	v_add_f32_e32 v74, 1.0, v74
	v_log_f32_e32 v74, v74
	v_cndmask_b32_e64 v71, 0, -v71, s[36:37]
	v_add_f32_e32 v70, v71, v70
	v_cndmask_b32_e64 v75, 0, -v74, s[38:39]
	v_cvt_pk_bf16_f32 v74, v71, v75
	v_add_f32_e32 v76, v75, v70
	v_lshlrev_b32_e32 v70, 16, v74
	v_sub_f32_e32 v70, v71, v70
	v_and_b32_e32 v71, 0xffff0000, v74
	v_sub_f32_e32 v71, v75, v71
	v_cvt_pk_bf16_f32 v70, v70, v71
	s_nop 0
	v_min_f32_e32 v158, 0x42c80000, v78
	v_add_u32_e32 v71, 0x5a, v143
	v_cmp_lt_i32_e64 s[2:3], v71, v176
	v_exp_f32_e32 v71, v158
	s_or_b64 s[40:41], s[44:45], s[2:3]
	v_add_f32_e32 v71, 1.0, v71
	v_log_f32_e32 v71, v71
	s_nop 0
	v_cndmask_b32_e64 v71, 0, -v71, s[40:41]
	v_add_f32_e32 v75, v71, v76
	s_nop 0
	v_min_f32_e32 v159, 0x42c80000, v79
	v_add_u32_e32 v76, 0x5b, v143
	v_cmp_lt_i32_e64 s[2:3], v76, v176
	v_exp_f32_e32 v76, v159
	s_or_b64 s[42:43], s[44:45], s[2:3]
	v_add_f32_e32 v76, 1.0, v76
	v_log_f32_e32 v76, v76
	s_nop 0
	v_cndmask_b32_e64 v76, 0, -v76, s[42:43]
	v_add_f32_e32 v77, v76, v75
	v_cvt_pk_bf16_f32 v75, v71, v76
	v_lshlrev_b32_e32 v78, 16, v75
	v_sub_f32_e32 v71, v71, v78
	v_and_b32_e32 v78, 0xffff0000, v75
	v_sub_f32_e32 v76, v76, v78
	v_cvt_pk_bf16_f32 v71, v71, v76
	v_add_u32_e32 v76, 0x60, v143
	v_cmp_lt_i32_e64 s[2:3], v76, v176
	s_or_b64 s[46:47], s[44:45], s[2:3]
	v_cmp_lt_i32_e64 s[2:3], v49, v176
	v_exp_f32_e32 v49, v157
	s_or_b64 s[48:49], s[44:45], s[2:3]
	v_cndmask_b32_e64 v48, 0, -v48, s[46:47]
	v_add_f32_e32 v76, v48, v77
	v_add_f32_e32 v49, 1.0, v49
	v_log_f32_e32 v49, v49
	s_nop 0
	v_cndmask_b32_e64 v49, 0, -v49, s[48:49]
	v_cvt_pk_bf16_f32 v136, v48, v49
	v_add_f32_e32 v77, v49, v76
	v_lshlrev_b32_e32 v76, 16, v136
	v_sub_f32_e32 v48, v48, v76
	v_and_b32_e32 v76, 0xffff0000, v136
	v_sub_f32_e32 v49, v49, v76
	v_cvt_pk_bf16_f32 v76, v48, v49
	s_nop 0
	v_min_f32_e32 v160, 0x42c80000, v50
	v_add_u32_e32 v48, 0x62, v143
	s_nop 0
	v_cmp_lt_i32_e64 s[2:3], v48, v176
	v_min_f32_e32 v161, 0x42c80000, v51
	v_add_u32_e32 v50, 0x63, v143
	s_or_b64 s[50:51], s[44:45], s[2:3]
	v_exp_f32_e32 v48, v160
	v_cmp_lt_i32_e64 s[2:3], v50, v176
	v_exp_f32_e32 v50, v161
	s_or_b64 s[52:53], s[44:45], s[2:3]
	v_add_f32_e32 v48, 1.0, v48
	v_log_f32_e32 v48, v48
	v_add_f32_e32 v50, 1.0, v50
	v_log_f32_e32 v50, v50
	v_cndmask_b32_e64 v48, 0, -v48, s[50:51]
	v_add_f32_e32 v49, v48, v77
	v_cndmask_b32_e64 v50, 0, -v50, s[52:53]
	v_cvt_pk_bf16_f32 v137, v48, v50
	v_lshlrev_b32_e32 v51, 16, v137
	v_sub_f32_e32 v48, v48, v51
	v_and_b32_e32 v51, 0xffff0000, v137
	v_add_f32_e32 v49, v50, v49
	v_sub_f32_e32 v50, v50, v51
	v_cvt_pk_bf16_f32 v77, v48, v50
	s_nop 0
	v_min_f32_e32 v162, 0x42c80000, v52
	v_add_u32_e32 v48, 0x68, v143
	s_nop 0
	v_cmp_lt_i32_e64 s[2:3], v48, v176
	v_min_f32_e32 v163, 0x42c80000, v53
	v_add_u32_e32 v50, 0x69, v143
	s_or_b64 s[54:55], s[44:45], s[2:3]
	v_exp_f32_e32 v48, v162
	v_cmp_lt_i32_e64 s[2:3], v50, v176
	v_exp_f32_e32 v50, v163
	s_or_b64 s[56:57], s[44:45], s[2:3]
	v_add_f32_e32 v48, 1.0, v48
	v_log_f32_e32 v48, v48
	v_add_f32_e32 v50, 1.0, v50
	v_log_f32_e32 v50, v50
	v_pk_add_f32 v[52:53], v[152:153], v[88:89] op_sel_hi:[0,1]
	v_cndmask_b32_e64 v48, 0, -v48, s[54:55]
	v_add_f32_e32 v49, v48, v49
	v_cndmask_b32_e64 v50, 0, -v50, s[56:57]
	v_cvt_pk_bf16_f32 v138, v48, v50
	v_lshlrev_b32_e32 v51, 16, v138
	v_sub_f32_e32 v48, v48, v51
	v_and_b32_e32 v51, 0xffff0000, v138
	v_add_f32_e32 v49, v50, v49
	v_sub_f32_e32 v50, v50, v51
	v_cvt_pk_bf16_f32 v78, v48, v50
	s_nop 0
	v_min_f32_e32 v164, 0x42c80000, v54
	v_add_u32_e32 v48, 0x6a, v143
	s_nop 0
	v_cmp_lt_i32_e64 s[2:3], v48, v176
	v_min_f32_e32 v165, 0x42c80000, v55
	v_add_u32_e32 v50, 0x6b, v143
	s_or_b64 s[58:59], s[44:45], s[2:3]
	v_exp_f32_e32 v48, v164
	v_cmp_lt_i32_e64 s[2:3], v50, v176
	v_exp_f32_e32 v50, v165
	s_or_b64 s[60:61], s[44:45], s[2:3]
	v_add_f32_e32 v48, 1.0, v48
	v_log_f32_e32 v48, v48
	v_add_f32_e32 v50, 1.0, v50
	v_log_f32_e32 v50, v50
	v_pk_add_f32 v[54:55], v[152:153], v[90:91] op_sel_hi:[0,1]
	v_cndmask_b32_e64 v48, 0, -v48, s[58:59]
	v_add_f32_e32 v49, v48, v49
	v_cndmask_b32_e64 v50, 0, -v50, s[60:61]
	v_cvt_pk_bf16_f32 v139, v48, v50
	v_lshlrev_b32_e32 v51, 16, v139
	v_sub_f32_e32 v48, v48, v51
	v_and_b32_e32 v51, 0xffff0000, v139
	v_add_f32_e32 v49, v50, v49
	v_sub_f32_e32 v50, v50, v51
	v_cvt_pk_bf16_f32 v79, v48, v50
	s_nop 0
	v_min_f32_e32 v166, 0x42c80000, v56
	v_add_u32_e32 v48, 0x70, v143
	s_nop 0
	v_cmp_lt_i32_e64 s[2:3], v48, v176
	v_min_f32_e32 v167, 0x42c80000, v57
	v_add_u32_e32 v50, 0x71, v143
	s_or_b64 s[62:63], s[44:45], s[2:3]
	v_exp_f32_e32 v48, v166
	v_cmp_lt_i32_e64 s[2:3], v50, v176
	v_exp_f32_e32 v50, v167
	s_or_b64 s[64:65], s[44:45], s[2:3]
	v_add_f32_e32 v48, 1.0, v48
	v_log_f32_e32 v48, v48
	v_add_f32_e32 v50, 1.0, v50
	v_log_f32_e32 v50, v50
	v_pk_add_f32 v[56:57], v[152:153], v[92:93] op_sel_hi:[0,1]
	v_cndmask_b32_e64 v48, 0, -v48, s[62:63]
; #define MFMA32(a, b, c) __builtin_amdgcn_mfma_f32_32x32x16_bf16((a), (b), (c), 0, 0, 0)
; DI unsigned pk_bf16(float lo, float hi) { f32x2 v = {lo, hi}; bf2_t b = __builtin_convertvector(v, bf2_t); return __builtin_bit_cast(unsigned, b); }
; DI int crow(int i, int h) { return (i & 3) + 8 * (i >> 2) + 4 * h; }
; DI float fast_exp2(float x) { return __builtin_amdgcn_exp2f(x); }
; template <int DQK, bool SB, bool SMAX>
; DI void attn_item(const Params& p, char* smem, int bh, int qb, float Mb) {
;     ...
;         tsum += other_half(tsum);
; #pragma unroll
;         for (int s = 0; s < 2; ++s) {
;           ca[0] = MFMA32(tri[s], hi[s], ca[0]);
;           ca[0] = MFMA32(tri[s], lo[s], ca[0]);
;           ca[0] = MFMA32(ones, hi[2 + s], ca[0]);
;           ca[0] = MFMA32(ones, lo[2 + s], ca[0]);
;           ca[1] = MFMA32(tri[s], hi[2 + s], ca[1]);
;           ca[1] = MFMA32(tri[s], lo[2 + s], ca[1]);
;         }
; #pragma unroll
;         for (int kb = 0; kb < 2; ++kb)
; #pragma unroll
;           for (int i = 0; i < 16; ++i) {
;             const int key = kb0 + kb * 32 + crow(i, h);
;             const bool valid = !diag || (key < query);
;             st[kb][i] = valid ? fast_exp2(ca[kb][i]) : 0.f;
;           }
;         carry += tsum;
;     ...
; #pragma unroll
;           for (int e = 0; e < 4; ++e) w[e] = pk_bf16(st[kb][8 * s + 2 * e], st[kb][8 * s + 2 * e + 1]);
;           pk[kb * 2 + s] = __builtin_bit_cast(bf16x8, w);
;         }
; #pragma unroll
;       for (int kk = 0; kk < 4; ++kk)
; #pragma unroll
;         for (int db = 0; db < 2; ++db) {
;           const s16x4 v0 = __builtin_amdgcn_ds_read_tr16_b64_v4i16((lds_s16x4*)(vc + voff + (16 * kk) * VSTR + 32 * db));
;           const s16x4 v1 = __builtin_amdgcn_ds_read_tr16_b64_v4i16((lds_s16x4*)(vc + voff + (16 * kk + 8) * VSTR + 32 * db));
;           const bf16x8 vf = __builtin_shufflevector(v0, v1, 0, 1, 2, 3, 4, 5, 6, 7);
;           O[db] = MFMA32(vf, pk[kk], O[db]);
	v_add_f32_e32 v49, v48, v49
	v_cndmask_b32_e64 v50, 0, -v50, s[64:65]
	v_cvt_pk_bf16_f32 v140, v48, v50
	v_lshlrev_b32_e32 v51, 16, v140
	v_sub_f32_e32 v48, v48, v51
	v_and_b32_e32 v51, 0xffff0000, v140
	v_add_f32_e32 v49, v50, v49
	v_sub_f32_e32 v50, v50, v51
	v_cvt_pk_bf16_f32 v144, v48, v50
	s_nop 0
	v_min_f32_e32 v168, 0x42c80000, v58
	v_add_u32_e32 v48, 0x72, v143
	s_nop 0
	v_cmp_lt_i32_e64 s[2:3], v48, v176
	v_min_f32_e32 v169, 0x42c80000, v59
	v_add_u32_e32 v50, 0x73, v143
	s_or_b64 s[66:67], s[44:45], s[2:3]
	v_exp_f32_e32 v48, v168
	v_cmp_lt_i32_e64 s[2:3], v50, v176
	v_exp_f32_e32 v50, v169
	s_or_b64 s[68:69], s[44:45], s[2:3]
	v_add_f32_e32 v48, 1.0, v48
	v_log_f32_e32 v48, v48
	v_add_f32_e32 v50, 1.0, v50
	v_log_f32_e32 v50, v50
	v_pk_add_f32 v[58:59], v[152:153], v[94:95] op_sel_hi:[0,1]
	v_cndmask_b32_e64 v48, 0, -v48, s[66:67]
	v_add_f32_e32 v49, v48, v49
	v_cndmask_b32_e64 v50, 0, -v50, s[68:69]
	v_cvt_pk_bf16_f32 v141, v48, v50
	v_lshlrev_b32_e32 v51, 16, v141
	v_sub_f32_e32 v48, v48, v51
	v_and_b32_e32 v51, 0xffff0000, v141
	v_add_f32_e32 v49, v50, v49
	v_sub_f32_e32 v50, v50, v51
	v_cvt_pk_bf16_f32 v145, v48, v50
	s_nop 0
	v_min_f32_e32 v170, 0x42c80000, v60
	v_add_u32_e32 v48, 0x78, v143
	s_nop 0
	v_cmp_lt_i32_e64 s[2:3], v48, v176
	v_min_f32_e32 v171, 0x42c80000, v61
	v_add_u32_e32 v50, 0x79, v143
	s_or_b64 s[70:71], s[44:45], s[2:3]
	v_exp_f32_e32 v48, v170
	v_cmp_lt_i32_e64 s[2:3], v50, v176
	v_exp_f32_e32 v50, v171
	s_or_b64 s[72:73], s[44:45], s[2:3]
	v_add_f32_e32 v48, 1.0, v48
	v_log_f32_e32 v48, v48
	v_add_f32_e32 v50, 1.0, v50
	v_log_f32_e32 v50, v50
	v_pk_add_f32 v[60:61], v[152:153], v[154:155] op_sel_hi:[0,1]
	v_cndmask_b32_e64 v48, 0, -v48, s[70:71]
	v_add_f32_e32 v49, v48, v49
	v_cndmask_b32_e64 v50, 0, -v50, s[72:73]
	v_cvt_pk_bf16_f32 v142, v48, v50
	v_lshlrev_b32_e32 v51, 16, v142
	v_sub_f32_e32 v48, v48, v51
	v_and_b32_e32 v51, 0xffff0000, v142
	v_add_f32_e32 v49, v50, v49
	v_sub_f32_e32 v50, v50, v51
	v_cvt_pk_bf16_f32 v146, v48, v50
	s_nop 0
	v_min_f32_e32 v182, 0x42c80000, v62
	v_add_u32_e32 v48, 0x7a, v143
	s_nop 0
	v_cmp_lt_i32_e64 s[2:3], v48, v176
	v_min_f32_e32 v183, 0x42c80000, v63
	v_add_u32_e32 v50, 0x7b, v143
	s_or_b64 s[74:75], s[44:45], s[2:3]
	v_exp_f32_e32 v48, v182
	v_cmp_lt_i32_e64 s[2:3], v50, v176
	v_exp_f32_e32 v50, v183
	s_or_b64 s[44:45], s[44:45], s[2:3]
	v_add_f32_e32 v48, 1.0, v48
	v_log_f32_e32 v48, v48
	v_add_f32_e32 v50, 1.0, v50
	v_log_f32_e32 v50, v50
	v_pk_add_f32 v[62:63], v[152:153], v[158:159] op_sel_hi:[0,1]
	v_cndmask_b32_e64 v48, 0, -v48, s[74:75]
	v_add_f32_e32 v49, v48, v49
	v_cndmask_b32_e64 v50, 0, -v50, s[44:45]
	v_cvt_pk_bf16_f32 v143, v48, v50
	v_add_f32_e32 v184, v50, v49
	v_lshlrev_b32_e32 v49, 16, v143
	v_sub_f32_e32 v48, v48, v49
	v_and_b32_e32 v49, 0xffff0000, v143
	v_sub_f32_e32 v49, v50, v49
	v_cvt_pk_bf16_f32 v147, v48, v49
	v_mov_b32_e32 v48, v184
	v_mov_b32_e32 v49, v184
	s_nop 1
	v_permlane32_swap_b32_e32 v48, v49
	v_cndmask_b32_e64 v185, v48, v49, s[8:9]
	v_pk_add_f32 v[50:51], v[152:153], v[86:87] op_sel_hi:[0,1]
	v_pk_add_f32 v[48:49], v[152:153], v[84:85] op_sel_hi:[0,1]
	v_pk_add_f32 v[94:95], v[152:153], v[182:183] op_sel_hi:[0,1]
	v_pk_add_f32 v[92:93], v[152:153], v[170:171] op_sel_hi:[0,1]
	v_mfma_f32_32x32x16_bf16 v[48:63], v[96:99], v[80:83], v[48:63]
	v_add_f32_e64 v90, v152, v168
	v_add_f32_e64 v91, v152, v169
	v_add_f32_e64 v88, v152, v166
	v_add_f32_e64 v89, v152, v167
	v_add_f32_e64 v86, v152, v164
	v_add_f32_e64 v87, v152, v165
	v_pk_add_f32 v[84:85], v[152:153], v[162:163] op_sel_hi:[0,1]
	v_pk_add_f32 v[82:83], v[152:153], v[160:161] op_sel_hi:[0,1]
	v_pk_add_f32 v[80:81], v[152:153], v[156:157] op_sel_hi:[0,1]
	v_mfma_f32_32x32x16_bf16 v[48:63], v[96:99], v[64:67], v[48:63]
	v_mov_b64_e32 v[64:65], s[96:97]
	v_mov_b64_e32 v[66:67], s[98:99]
	s_nop 1
	v_mfma_f32_32x32x16_bf16 v[48:63], v[64:67], v[136:139], v[48:63]
	v_mfma_f32_32x32x16_bf16 v[48:63], v[64:67], v[76:79], v[48:63]
	v_mfma_f32_32x32x16_bf16 v[48:63], v[100:103], v[72:75], v[48:63]
	v_mfma_f32_32x32x16_bf16 v[48:63], v[100:103], v[68:71], v[48:63]
	v_mfma_f32_32x32x16_bf16 v[48:63], v[64:67], v[140:143], v[48:63]
	v_mfma_f32_32x32x16_bf16 v[48:63], v[64:67], v[144:147], v[48:63]
	v_mfma_f32_32x32x16_bf16 v[80:95], v[96:99], v[136:139], v[80:95]
	s_nop 10
	v_exp_f32_e32 v48, v48
	s_nop 0
	v_cndmask_b32_e32 v64, 0, v48, vcc
	v_exp_f32_e32 v48, v49
	v_mfma_f32_32x32x16_bf16 v[80:95], v[96:99], v[76:79], v[80:95]
	v_cndmask_b32_e64 v65, 0, v48, s[12:13]
	v_exp_f32_e32 v48, v50
	s_nop 0
	v_cndmask_b32_e64 v66, 0, v48, s[14:15]
	v_exp_f32_e32 v48, v51
	v_mfma_f32_32x32x16_bf16 v[80:95], v[100:103], v[140:143], v[80:95]
	v_cndmask_b32_e64 v67, 0, v48, s[16:17]
	v_exp_f32_e32 v48, v52
	s_nop 0
	v_cndmask_b32_e64 v68, 0, v48, s[18:19]
	v_exp_f32_e32 v48, v53
	v_mfma_f32_32x32x16_bf16 v[80:95], v[100:103], v[144:147], v[80:95]
	v_cndmask_b32_e64 v69, 0, v48, s[20:21]
	v_exp_f32_e32 v48, v54
	s_nop 0
	v_cndmask_b32_e64 v70, 0, v48, s[22:23]
	v_exp_f32_e32 v48, v55
	s_nop 6
	v_exp_f32_e32 v53, v85
	v_add_u32_e32 v85, v198, v200
	ds_read_b64_tr_b16 v[140:141], v85 offset:27648
	ds_read_b64_tr_b16 v[142:143], v85 offset:28800
	v_cndmask_b32_e64 v71, 0, v48, s[24:25]
	v_exp_f32_e32 v48, v56
	v_exp_f32_e32 v54, v86
	v_exp_f32_e32 v55, v87
	v_exp_f32_e32 v56, v88
	v_cndmask_b32_e64 v72, 0, v48, s[26:27]
	v_exp_f32_e32 v48, v57
	v_exp_f32_e32 v57, v89
	v_cvt_pk_bf16_f32 v86, v64, v65
	v_cvt_pk_bf16_f32 v87, v66, v67
	v_cndmask_b32_e64 v73, 0, v48, s[28:29]
	v_exp_f32_e32 v48, v58
	v_cvt_pk_bf16_f32 v88, v68, v69
	v_cvt_pk_bf16_f32 v89, v70, v71
	v_exp_f32_e32 v58, v90
	v_cndmask_b32_e64 v74, 0, v48, s[30:31]
	v_exp_f32_e32 v48, v59
	s_waitcnt lgkmcnt(0)
; #define MFMA32(a, b, c) __builtin_amdgcn_mfma_f32_32x32x16_bf16((a), (b), (c), 0, 0, 0)
; DI unsigned pk_bf16(float lo, float hi) { f32x2 v = {lo, hi}; bf2_t b = __builtin_convertvector(v, bf2_t); return __builtin_bit_cast(unsigned, b); }
; template <int DQK, bool SB, bool SMAX>
; DI void attn_item(const Params& p, char* smem, int bh, int qb, float Mb) {
;     ...
;         carry += tsum;
;       }
; #pragma unroll
;       for (int kb = 0; kb < 2; ++kb)
; #pragma unroll
;         for (int s = 0; s < 2; ++s) {
;           u32x4 w;
; #pragma unroll
;           for (int e = 0; e < 4; ++e) w[e] = pk_bf16(st[kb][8 * s + 2 * e], st[kb][8 * s + 2 * e + 1]);
;           pk[kb * 2 + s] = __builtin_bit_cast(bf16x8, w);
;         }
; #pragma unroll
;       for (int kk = 0; kk < 4; ++kk)
; #pragma unroll
;         for (int db = 0; db < 2; ++db) {
;           const s16x4 v0 = __builtin_amdgcn_ds_read_tr16_b64_v4i16((lds_s16x4*)(vc + voff + (16 * kk) * VSTR + 32 * db));
;           const s16x4 v1 = __builtin_amdgcn_ds_read_tr16_b64_v4i16((lds_s16x4*)(vc + voff + (16 * kk + 8) * VSTR + 32 * db));
;           const bf16x8 vf = __builtin_shufflevector(v0, v1, 0, 1, 2, 3, 4, 5, 6, 7);
;           O[db] = MFMA32(vf, pk[kk], O[db]);
;         }
	v_mfma_f32_32x32x16_bf16 v[32:47], v[140:143], v[86:89], v[32:47]
	ds_read_b64_tr_b16 v[140:141], v85 offset:27712
	ds_read_b64_tr_b16 v[142:143], v85 offset:28864
	v_exp_f32_e32 v59, v91
	v_cndmask_b32_e64 v75, 0, v48, s[34:35]
	v_exp_f32_e32 v48, v60
	v_exp_f32_e32 v60, v92
	v_cvt_pk_bf16_f32 v90, v72, v73
	v_cvt_pk_bf16_f32 v91, v74, v75
	v_cndmask_b32_e64 v76, 0, v48, s[36:37]
	v_exp_f32_e32 v48, v61
	s_waitcnt lgkmcnt(0)
	v_mfma_f32_32x32x16_bf16 v[16:31], v[140:143], v[86:89], v[16:31]
	ds_read_b64_tr_b16 v[86:87], v85 offset:29952
	ds_read_b64_tr_b16 v[88:89], v85 offset:31104
	v_exp_f32_e32 v61, v93
	v_cndmask_b32_e64 v77, 0, v48, s[38:39]
	v_exp_f32_e32 v48, v62
	v_cvt_pk_bf16_f32 v92, v76, v77
	v_exp_f32_e32 v49, v81
	v_exp_f32_e32 v50, v82
	v_cndmask_b32_e64 v78, 0, v48, s[40:41]
	v_exp_f32_e32 v48, v63
	v_exp_f32_e32 v51, v83
	v_exp_f32_e32 v52, v84
	v_cndmask_b32_e64 v49, 0, v49, s[48:49]
	v_cndmask_b32_e64 v79, 0, v48, s[42:43]
	v_cvt_pk_bf16_f32 v93, v78, v79
	v_exp_f32_e32 v48, v80
	v_cndmask_b32_e64 v50, 0, v50, s[50:51]
	s_waitcnt lgkmcnt(0)
	v_mfma_f32_32x32x16_bf16 v[32:47], v[86:89], v[90:93], v[32:47]
	ds_read_b64_tr_b16 v[86:87], v85 offset:30016
	ds_read_b64_tr_b16 v[88:89], v85 offset:31168
	v_cndmask_b32_e64 v48, 0, v48, s[46:47]
	v_cndmask_b32_e64 v51, 0, v51, s[52:53]
	v_cndmask_b32_e64 v52, 0, v52, s[54:55]
	v_cndmask_b32_e64 v53, 0, v53, s[56:57]
	v_cndmask_b32_e64 v54, 0, v54, s[58:59]
	v_cndmask_b32_e64 v55, 0, v55, s[60:61]
	s_waitcnt lgkmcnt(0)
	v_mfma_f32_32x32x16_bf16 v[16:31], v[86:89], v[90:93], v[16:31]
	ds_read_b64_tr_b16 v[86:87], v85 offset:32256
	ds_read_b64_tr_b16 v[88:89], v85 offset:33408
	v_cvt_pk_bf16_f32 v136, v48, v49
	v_cvt_pk_bf16_f32 v137, v50, v51
	v_cvt_pk_bf16_f32 v138, v52, v53
	v_cvt_pk_bf16_f32 v139, v54, v55
	v_exp_f32_e32 v62, v94
	v_exp_f32_e32 v63, v95
	s_waitcnt lgkmcnt(0)
	v_mfma_f32_32x32x16_bf16 v[32:47], v[86:89], v[136:139], v[32:47]
	ds_read_b64_tr_b16 v[86:87], v85 offset:32320
	ds_read_b64_tr_b16 v[88:89], v85 offset:33472
	v_cndmask_b32_e64 v56, 0, v56, s[62:63]
	v_cndmask_b32_e64 v57, 0, v57, s[64:65]
	v_cndmask_b32_e64 v58, 0, v58, s[66:67]
	v_cndmask_b32_e64 v59, 0, v59, s[68:69]
	v_cndmask_b32_e64 v60, 0, v60, s[70:71]
	v_cndmask_b32_e64 v61, 0, v61, s[72:73]
	s_waitcnt lgkmcnt(0)
	v_mfma_f32_32x32x16_bf16 v[16:31], v[86:89], v[136:139], v[16:31]
	ds_read_b64_tr_b16 v[86:87], v85 offset:34560
	ds_read_b64_tr_b16 v[88:89], v85 offset:35712
	v_cndmask_b32_e64 v62, 0, v62, s[74:75]
	v_cndmask_b32_e64 v63, 0, v63, s[44:45]
	v_cvt_pk_bf16_f32 v80, v56, v57
	v_cvt_pk_bf16_f32 v81, v58, v59
	v_cvt_pk_bf16_f32 v82, v60, v61
	v_cvt_pk_bf16_f32 v83, v62, v63
	v_add_f32_e32 v84, v184, v185
	v_add_f32_e32 v152, v152, v84
	s_waitcnt lgkmcnt(0)
	v_mfma_f32_32x32x16_bf16 v[32:47], v[86:89], v[80:83], v[32:47]
	ds_read_b64_tr_b16 v[86:87], v85 offset:34624
	ds_read_b64_tr_b16 v[88:89], v85 offset:35776
	s_waitcnt lgkmcnt(0)
	v_mfma_f32_32x32x16_bf16 v[16:31], v[86:89], v[80:83], v[16:31]
